# MLA LDS copy in the P*V chain: two ds_writes per MFMA gap right behind the first MFMAs (addresses formed before the chain)
# baseline (speedup 1.0000x reference)
; #define LAS __attribute__((address_space(3)))
; template <int DQK, int DV, bool CAUSAL, int KT, bool PRIO>
; DI void attn_unit(const bf16_t* Qb, int qpitch, const bf16_t* Kb, int kpitch, const bf16_t* Vtb, int vpitch, bf16_t* Ob, int opitch, int q0, int nt, LAS unsigned char* lds, float kbound, const float* qgain, const int* qpos, float qscale) {
;     ...
;     auto lstore = [&](int buf) {
; #pragma unroll
;         for (int i = 0; i < NKR; ++i) { const int c = tid + i * 512; if (NKC % 512 == 0 || c < NKC) *(LAS u32x4*)(lds + buf * KBUF + (c / KCH) * KS + (c % KCH) * 16) = kreg[i]; }
; #pragma unroll
;         for (int i = 0; i < NVR; ++i) { const int c = tid + i * 512; LAS unsigned char* p = lds + VOFF + buf * VBUF + (c / VCH) * VS + (c % VCH) * 16;
;             *(LAS u32x2*)p = (u32x2){vreg[i].x, vreg[i].y}; *(LAS u32x2*)(p + 8) = (u32x2){vreg[i].z, vreg[i].w}; }
;     ...
;                     float ps = 0.f;
; #pragma unroll
;                     for (int i = 0; i < 16; ++i) { s0[i] = __builtin_amdgcn_exp2f(s0[i]); ps += s0[i]; asm volatile("" : "+v"(ps)); }
; #pragma unroll
;                     for (int i = 0; i < 16; ++i) { s1[i] = __builtin_amdgcn_exp2f(s1[i]); ps += s1[i]; asm volatile("" : "+v"(ps)); }
;                     lrun += ps;
;                     bf16x8 pf[4];
; #pragma unroll
;                     for (int sf = 0; sf < 2; ++sf) {
;                         u32x4 pw; pw.x = pk2(s0[8 * sf], s0[8 * sf + 1]); pw.y = pk2(s0[8 * sf + 2], s0[8 * sf + 3]); pw.z = pk2(s0[8 * sf + 4], s0[8 * sf + 5]); pw.w = pk2(s0[8 * sf + 6], s0[8 * sf + 7]); pf[sf] = __builtin_bit_cast(bf16x8, pw);
;                         u32x4 pv; pv.x = pk2(s1[8 * sf], s1[8 * sf + 1]); pv.y = pk2(s1[8 * sf + 2], s1[8 * sf + 3]); pv.z = pk2(s1[8 * sf + 4], s1[8 * sf + 5]); pv.w = pk2(s1[8 * sf + 6], s1[8 * sf + 7]); pf[2 + sf] = __builtin_bit_cast(bf16x8, pv);
;                     }
;                     __builtin_amdgcn_sched_barrier(0); __builtin_amdgcn_s_setprio(1); __builtin_amdgcn_sched_barrier(0);
; #pragma unroll
;                     for (int q4 = 0; q4 < 4; ++q4)
; #pragma unroll
;                         for (int d = 0; d < NDB; ++d) o[d] = MFMA32(vf[q4][d], pf[q4], o[d]);
;                     __builtin_amdgcn_sched_barrier(0); __builtin_amdgcn_s_setprio(0); __builtin_amdgcn_sched_barrier(0);
.LBB0_1514:
	s_nop 7
	v_exp_f32_e32 v14, v80
	v_exp_f32_e32 v15, v81
	v_exp_f32_e32 v80, v82
	v_exp_f32_e32 v81, v83
	v_add_f32_e32 v82, 0, v14
	v_exp_f32_e32 v83, v84
	v_add_f32_e32 v82, v15, v82
	v_exp_f32_e32 v84, v85
	v_add_f32_e32 v82, v80, v82
	v_exp_f32_e32 v85, v86
	v_add_f32_e32 v82, v81, v82
	v_exp_f32_e32 v86, v87
	v_add_f32_e32 v82, v83, v82
	v_exp_f32_e32 v87, v88
	v_add_f32_e32 v82, v84, v82
	v_exp_f32_e32 v88, v89
	v_add_f32_e32 v82, v85, v82
	v_exp_f32_e32 v89, v90
	v_add_f32_e32 v82, v86, v82
	v_exp_f32_e32 v90, v91
	v_add_f32_e32 v82, v87, v82
	v_exp_f32_e32 v91, v92
	v_add_f32_e32 v82, v88, v82
	v_exp_f32_e32 v92, v93
	v_add_f32_e32 v82, v89, v82
	v_exp_f32_e32 v93, v94
	v_add_f32_e32 v82, v90, v82
	v_exp_f32_e32 v94, v95
	v_add_f32_e32 v82, v91, v82
	v_exp_f32_e32 v95, v64
	v_add_f32_e32 v82, v92, v82
	v_exp_f32_e32 v194, v66
	v_add_f32_e32 v82, v93, v82
	v_exp_f32_e32 v195, v67
	v_add_f32_e32 v64, v94, v82
	v_exp_f32_e32 v82, v65
	v_exp_f32_e32 v197, v68
	v_add_f32_e32 v64, v95, v64
	v_exp_f32_e32 v198, v69
	v_add_f32_e32 v64, v82, v64
	v_exp_f32_e32 v199, v70
	v_add_f32_e32 v64, v194, v64
	v_exp_f32_e32 v71, v71
	v_add_f32_e32 v64, v195, v64
	v_exp_f32_e32 v200, v72
	v_add_f32_e32 v64, v197, v64
	v_exp_f32_e32 v201, v73
	v_add_f32_e32 v64, v198, v64
	v_exp_f32_e32 v202, v74
	v_add_f32_e32 v64, v199, v64
	v_exp_f32_e32 v203, v75
	v_add_f32_e32 v64, v71, v64
	v_exp_f32_e32 v204, v76
	v_add_f32_e32 v64, v200, v64
	v_exp_f32_e32 v205, v77
	v_add_f32_e32 v64, v201, v64
	v_exp_f32_e32 v206, v78
	v_add_f32_e32 v64, v202, v64
	v_exp_f32_e32 v79, v79
	v_add_f32_e32 v64, v203, v64
	v_cvt_pk_bf16_f32 v65, v80, v81
	v_add_f32_e32 v64, v204, v64
	v_cvt_pk_bf16_f32 v66, v83, v84
	v_add_f32_e32 v64, v205, v64
	v_cvt_pk_bf16_f32 v67, v85, v86
	v_add_f32_e32 v64, v206, v64
	v_cvt_pk_bf16_f32 v68, v95, v82
	v_add_f32_e32 v207, v79, v64
	v_cvt_pk_bf16_f32 v64, v14, v15
	v_cvt_pk_bf16_f32 v69, v194, v195
	v_cvt_pk_bf16_f32 v70, v197, v198
	v_cvt_pk_bf16_f32 v71, v199, v71
	v_cvt_pk_bf16_f32 v72, v87, v88
	v_cvt_pk_bf16_f32 v73, v89, v90
	v_cvt_pk_bf16_f32 v74, v91, v92
	v_cvt_pk_bf16_f32 v75, v93, v94
	v_cvt_pk_bf16_f32 v76, v200, v201
	v_cvt_pk_bf16_f32 v77, v202, v203
	v_cvt_pk_bf16_f32 v78, v204, v205
	v_cvt_pk_bf16_f32 v79, v206, v79
	s_xor_b32 s100, s75, 1
	s_mul_i32 s101, s100, 0x6800
	s_mulk_i32 s100, 0xdc00
	v_add3_u32 v250, s101, v178, v179
	v_add3_u32 v251, s101, v181, v182
	v_add3_u32 v252, s101, v183, v184
	s_add_i32 s101, s101, s100
	v_add_u32_e32 v253, s101, v185
	v_add_u32_e32 v254, s101, v187
	v_add3_u32 v253, v253, v186, s57
	v_add3_u32 v254, v254, v188, s57
	s_setprio 1
	s_waitcnt lgkmcnt(0)
	s_waitcnt vmcnt(0)
	v_mfma_f32_32x32x16_bf16 v[32:47], v[156:159], v[64:67], v[32:47]
	v_add_f32_e32 v0, v0, v207
	ds_write_b128 v250, v[96:99]
	ds_write_b128 v251, v[100:103]
	v_mfma_f32_32x32x16_bf16 v[16:31], v[152:155], v[64:67], v[16:31]
	ds_write_b128 v252, v[104:107]
	ds_write2_b64 v253, v[108:109], v[110:111] offset1:2
	v_mfma_f32_32x32x16_bf16 v[32:47], v[140:143], v[72:75], v[32:47]
	ds_write2_b64 v254, v[112:113], v[114:115] offset1:2
	v_mfma_f32_32x32x16_bf16 v[16:31], v[148:151], v[72:75], v[16:31]
	v_mfma_f32_32x32x16_bf16 v[32:47], v[144:147], v[68:71], v[32:47]
	v_mfma_f32_32x32x16_bf16 v[16:31], v[10:13], v[68:71], v[16:31]
	v_mfma_f32_32x32x16_bf16 v[32:47], v[6:9], v[76:79], v[32:47]
	v_mfma_f32_32x32x16_bf16 v[16:31], v[2:5], v[76:79], v[16:31]
	s_setprio 0
	s_branch .LBB0_1493
	s_nop 0
	s_nop 0
	s_nop 0
	s_nop 0
	s_nop 0
	s_nop 0
	s_nop 0
	s_nop 0
	s_nop 0
	s_nop 0
	s_nop 0
	s_nop 0
	s_nop 0
